# token-prep phase: per-token rows rebalanced so the 128 workgroups that carry a fifth 16-token tile take fewer rows
# baseline (speedup 1.0000x reference)
; DI float bf2f(u16 h) { return __uint_as_float(((unsigned)h) << 16); }
; DI u16 f2bf(float a) { return (u16)(pack2(a, 0.f) & 0xffffu); }
; DI void phase_tokA(const Params& p, int l) {
;     ...
;   for (int r = blk__ * 4 + wave; r < NT; r += gridDim.x * 4) {
;     ...
;     for (int gi = 0; gi < 4; ++gi) {
;       const int half = 1 << gi;
;       const int lo = max(t - half, 0), hi = min(t + half, Ls);
;       float sm = 0.f;
; #pragma unroll
;       for (int j = 0; j < 2 * half; ++j) {
;         const int q = t - half + j;
;         sm += (q >= 0 && q < Ls) ? bf2f(pw[2 * half - 2 + j]) : 0.f;
;       }
;       pv[gi] = sm / (float)(hi - lo) - bf2f(pc[gi]);
;     }
;     if (lane == 0) { rsq[r] = rq; rskv[r] = rkv; }
;     if (lane < 32) krb[(size_t)r * 32 + d] = f2bf(outv);
; #pragma unroll
;     for (int gi = 0; gi < 4; ++gi) pooled[(size_t)r * 256 + gi * 64 + lane] = f2bf(pv[gi]);
.LBB0_757:
	s_or_b64 exec, exec, s[8:9]
	v_add_u32_e32 v12, -1, v35
	v_cmp_lt_u32_e64 s[8:9], v12, v34
	v_max_i32_e32 v12, 0, v12
	s_waitcnt lgkmcnt(0)
	v_min_u32_e32 v31, v41, v34
	v_sub_u32_e32 v12, v31, v12
	v_lshlrev_b32_e32 v13, 16, v52
	v_cvt_f32_i32_e32 v12, v12
	v_add_f32_e32 v13, 0, v13
	v_lshlrev_b32_e32 v15, 16, v56
	v_cmp_lt_u32_e64 s[10:11], v35, v34
	v_cndmask_b32_e64 v13, 0, v13, s[8:9]
	v_lshlrev_b32_e32 v47, 16, v47
	v_cndmask_b32_e64 v15, 0, v15, s[10:11]
	v_add_f32_e32 v13, v13, v15
	v_div_scale_f32 v15, s[12:13], v12, v12, v13
	v_rcp_f32_e32 v31, v15
	v_add_f32_e32 v47, 0, v47
	v_lshlrev_b32_e32 v45, 16, v45
	v_cndmask_b32_e64 v45, 0, v45, s[8:9]
	v_fma_f32 v52, -v15, v31, 1.0
	v_fmac_f32_e32 v31, v52, v31
	v_div_scale_f32 v52, vcc, v13, v12, v13
	v_mul_f32_e32 v56, v52, v31
	v_fma_f32 v58, -v15, v56, v52
	v_fmac_f32_e32 v56, v58, v31
	v_fma_f32 v15, -v15, v56, v52
	v_div_fmas_f32 v15, v15, v31, v56
	v_add_u32_e32 v31, -2, v35
	v_cmp_lt_u32_e64 s[12:13], v31, v34
	v_max_i32_e32 v31, 0, v31
	v_lshlrev_b32_e32 v43, 16, v43
	v_cndmask_b32_e64 v47, 0, v47, s[12:13]
	v_add_f32_e32 v45, v47, v45
	v_min_u32_e32 v47, v49, v34
	v_sub_u32_e32 v31, v47, v31
	v_cndmask_b32_e64 v43, 0, v43, s[10:11]
	v_cvt_f32_i32_e32 v31, v31
	v_add_f32_e32 v43, v45, v43
	v_lshlrev_b32_e32 v45, 16, v53
	v_cmp_lt_u32_e64 s[14:15], v41, v34
	v_div_fixup_f32 v12, v15, v12, v13
	v_lshlrev_b32_e32 v13, 16, v38
	v_cndmask_b32_e64 v41, 0, v45, s[14:15]
	v_add_f32_e32 v41, v43, v41
	v_div_scale_f32 v43, s[18:19], v31, v31, v41
	v_rcp_f32_e32 v45, v43
	v_sub_f32_e32 v15, v12, v13
	v_lshlrev_b32_e32 v40, 16, v40
	v_cndmask_b32_e64 v40, 0, v40, s[10:11]
	v_fma_f32 v12, -v43, v45, 1.0
	v_fmac_f32_e32 v45, v12, v45
	v_div_scale_f32 v12, vcc, v41, v31, v41
	v_mul_f32_e32 v13, v12, v45
	v_fma_f32 v38, -v43, v13, v12
	v_fmac_f32_e32 v13, v38, v45
	v_fma_f32 v12, -v43, v13, v12
	v_div_fmas_f32 v12, v12, v45, v13
	v_add_u32_e32 v13, -4, v35
	v_lshlrev_b32_e32 v38, 16, v42
	v_add_u32_e32 v42, -3, v35
	v_add_f32_e32 v38, 0, v38
	v_cmp_lt_u32_e64 s[18:19], v13, v34
	v_lshlrev_b32_e32 v43, 16, v48
	v_cmp_lt_u32_e64 s[20:21], v42, v34
	v_cndmask_b32_e64 v38, 0, v38, s[18:19]
	v_lshlrev_b32_e32 v39, 16, v39
	v_cndmask_b32_e64 v42, 0, v43, s[20:21]
	v_add_f32_e32 v38, v38, v42
	v_lshlrev_b32_e32 v42, 16, v46
	v_cndmask_b32_e64 v42, 0, v42, s[12:13]
	v_add_f32_e32 v38, v38, v42
	v_lshlrev_b32_e32 v42, 16, v44
	v_cndmask_b32_e64 v42, 0, v42, s[8:9]
	v_add_f32_e32 v38, v38, v42
	v_add_f32_e32 v38, v38, v40
	v_cndmask_b32_e64 v39, 0, v39, s[14:15]
	v_max_i32_e32 v13, 0, v13
	v_min_u32_e32 v40, v17, v34
	v_add_f32_e32 v38, v38, v39
	v_lshlrev_b32_e32 v39, 16, v55
	v_cmp_lt_u32_e64 s[22:23], v49, v34
	v_sub_u32_e32 v13, v40, v13
	v_cvt_f32_i32_e32 v13, v13
	v_cndmask_b32_e64 v39, 0, v39, s[22:23]
	v_add_f32_e32 v38, v38, v39
	v_lshlrev_b32_e32 v39, 16, v57
	v_cmp_lt_u32_e64 s[24:25], v50, v34
	v_div_fixup_f32 v12, v12, v31, v41
	v_lshlrev_b32_e32 v31, 16, v37
	v_cndmask_b32_e64 v39, 0, v39, s[24:25]
	v_add_f32_e32 v38, v38, v39
	v_div_scale_f32 v39, s[34:35], v13, v13, v38
	v_rcp_f32_e32 v40, v39
	v_sub_f32_e32 v31, v12, v31
	v_lshlrev_b32_e32 v29, 16, v29
	v_cndmask_b32_e64 v29, 0, v29, s[18:19]
	v_fma_f32 v12, -v39, v40, 1.0
	v_fmac_f32_e32 v40, v12, v40
	v_div_scale_f32 v12, vcc, v38, v13, v38
	v_mul_f32_e32 v37, v12, v40
	v_fma_f32 v41, -v39, v37, v12
	v_fmac_f32_e32 v37, v41, v40
	v_fma_f32 v12, -v39, v37, v12
	v_div_fmas_f32 v12, v12, v40, v37
	v_add_u32_e32 v37, -8, v35
	v_lshlrev_b32_e32 v39, 16, v51
	v_add_f32_e32 v39, 0, v39
	v_cmp_lt_u32_e32 vcc, v37, v34
	v_add_u32_e32 v40, -7, v35
	v_lshlrev_b32_e32 v41, 16, v54
	v_cndmask_b32_e32 v39, 0, v39, vcc
	v_cmp_lt_u32_e32 vcc, v40, v34
	v_lshlrev_b32_e32 v28, 16, v28
	v_cndmask_b32_e64 v28, 0, v28, s[20:21]
	v_cndmask_b32_e32 v40, 0, v41, vcc
	v_add_f32_e32 v39, v39, v40
	v_add_u32_e32 v40, -6, v35
	v_lshlrev_b32_e32 v41, 16, v59
	v_cmp_lt_u32_e32 vcc, v40, v34
	v_lshlrev_b32_e32 v25, 16, v25
	v_cndmask_b32_e64 v25, 0, v25, s[12:13]
	v_cndmask_b32_e32 v40, 0, v41, vcc
	v_add_f32_e32 v39, v39, v40
	v_add_u32_e32 v40, -5, v35
	v_lshlrev_b32_e32 v41, 16, v60
	v_cmp_lt_u32_e32 vcc, v40, v34
	v_lshlrev_b32_e32 v24, 16, v24
	v_cndmask_b32_e64 v24, 0, v24, s[8:9]
	v_cndmask_b32_e32 v40, 0, v41, vcc
	v_add_f32_e32 v39, v39, v40
	v_add_f32_e32 v29, v39, v29
	v_add_f32_e32 v28, v29, v28
	v_add_f32_e32 v25, v28, v25
	v_lshlrev_b32_e32 v20, 16, v20
	v_add_f32_e32 v24, v25, v24
	v_cndmask_b32_e64 v20, 0, v20, s[10:11]
	v_lshlrev_b32_e32 v19, 16, v19
	v_add_f32_e32 v20, v24, v20
	v_cndmask_b32_e64 v19, 0, v19, s[14:15]
	v_lshlrev_b32_e32 v18, 16, v18
	v_add_f32_e32 v19, v20, v19
	v_cndmask_b32_e64 v18, 0, v18, s[22:23]
	v_lshlrev_b32_e32 v16, 16, v16
	v_add_f32_e32 v18, v19, v18
	v_cndmask_b32_e64 v16, 0, v16, s[24:25]
	v_add_f32_e32 v16, v18, v16
	v_lshlrev_b32_e32 v18, 16, v23
	v_cmp_lt_u32_e32 vcc, v17, v34
	v_lshlrev_b32_e32 v14, 16, v14
	v_div_fixup_f32 v12, v12, v13, v38
	v_cndmask_b32_e32 v17, 0, v18, vcc
	v_add_f32_e32 v16, v16, v17
	v_lshlrev_b32_e32 v17, 16, v27
	v_cmp_lt_u32_e32 vcc, v21, v34
	v_max_i32_e32 v18, 0, v37
	v_lshlrev_b32_e32 v11, 16, v11
	v_cndmask_b32_e32 v17, 0, v17, vcc
	v_add_f32_e32 v16, v16, v17
	v_lshlrev_b32_e32 v17, 16, v30
	v_cmp_lt_u32_e32 vcc, v26, v34
	v_sub_f32_e32 v11, v12, v11
	s_nop 0
	v_cndmask_b32_e32 v17, 0, v17, vcc
	v_add_f32_e32 v16, v16, v17
	v_add_u32_e32 v17, 8, v35
	v_min_u32_e32 v17, v17, v34
	v_sub_u32_e32 v17, v17, v18
	v_cvt_f32_i32_e32 v17, v17
	v_cmp_lt_u32_e32 vcc, v22, v34
	s_nop 1
	v_cndmask_b32_e32 v14, 0, v14, vcc
	v_add_f32_e32 v14, v16, v14
	v_div_scale_f32 v16, s[8:9], v17, v17, v14
	v_rcp_f32_e32 v18, v16
	s_mov_b32 s8, 0x87ff
	v_fma_f32 v12, -v16, v18, 1.0
	v_fmac_f32_e32 v18, v12, v18
	v_div_scale_f32 v12, vcc, v14, v17, v14
	v_mul_f32_e32 v13, v12, v18
	v_fma_f32 v19, -v16, v13, v12
	v_fmac_f32_e32 v13, v19, v18
	v_fma_f32 v12, -v16, v13, v12
	v_div_fmas_f32 v12, v12, v18, v13
	v_div_fixup_f32 v12, v12, v17, v14
	v_lshlrev_b32_e32 v13, 16, v36
	v_sub_f32_e32 v14, v12, v13
	v_lshlrev_b64 v[12:13], 9, v[2:3]
	v_lshl_add_u64 v[12:13], v[8:9], 0, v[12:13]
	v_cvt_pk_bf16_f32 v3, v15, s0
	flat_store_short v[12:13], v3
	v_cvt_pk_bf16_f32 v3, v31, s0
	v_add_u32_e32 v2, s36, v2
	s_cmpk_eq_i32 s36, 0x800
	s_cbranch_scc0 .Ltoka_p2
	v_readfirstlane_b32 s100, v2
	s_cmpk_lt_i32 s100, 0x5000
	s_cbranch_scc1 .Ltoka_p2
	s_movk_i32 s36, 0x600
	v_mov_b32_e32 v2, 0x8800
	s_cmpk_lt_i32 s2, 0x80
	s_cbranch_scc1 .Ltoka_p2
	v_ashrrev_i32_e32 v74, 6, v163
	v_lshl_add_u32 v2, s2, 2, v74
	v_add_u32_e32 v2, 0x4e00, v2
.Ltoka_p2:
	flat_store_short v[12:13], v3 offset:128
	v_cvt_pk_bf16_f32 v3, v11, s0
	v_cmp_lt_i32_e32 vcc, s8, v2
	flat_store_short v[12:13], v3 offset:256
	v_cvt_pk_bf16_f32 v3, v14, s0
	s_or_b64 s[28:29], vcc, s[28:29]
	flat_store_short v[12:13], v3 offset:384
	s_andn2_b64 exec, exec, s[28:29]
	s_cbranch_execz .LBB0_762
